# stack1 + thread-0 serialized polls parallelized (team XCC check, P7 cross-team wait) + vmcnt(1) after arrival atomic
# speedup vs baseline: 1.0013x; 1.0013x over previous
; __device__ __forceinline__ unsigned xb_add(unsigned* p, unsigned v) { return __hip_atomic_fetch_add(p, v, __ATOMIC_RELAXED, __HIP_MEMORY_SCOPE_AGENT); }
; __device__ __forceinline__ void xcd_barrier(const XcdBarrier& b) {
;     asm volatile("s_waitcnt vmcnt(0)" ::: "memory");
;     __syncthreads();
;     if (threadIdx.x == 0) {
;         unsigned* bar = b.bar;
;         __builtin_amdgcn_s_waitcnt(0);
;         unsigned nloc = b.st[0], nx = b.st[1];
;         if (nloc == 0u) { xcd_barrier_complete(bar, b.x, nloc, nx); b.st[0] = nloc; b.st[1] = nx; }
;         const unsigned old = xb_add(&bar[XB_XSUB(b.x)], 1u);
;         asm volatile("buffer_inv sc1" ::: "memory");
;         const unsigned gen = old / nloc;
;         if (old + 1u == (gen + 1u) * nloc) {
;             __builtin_amdgcn_fence(__ATOMIC_RELEASE, "agent");
;             asm volatile("s_waitcnt vmcnt(0)" ::: "memory");
;             const unsigned og = xb_add(&bar[XB_TOP], 1u);
.LBB0_82:
	s_lshl_b32 s3, s90, 8
	s_add_u32 s8, s58, s3
	s_addc_u32 s9, s59, 0
	v_mov_b32_e32 v2, 0x1000
	v_mov_b32_e32 v4, 1
	global_atomic_add v4, v2, v4, s[8:9] offset:1024 sc0
	v_cvt_f32_u32_e32 v2, v3
	v_sub_u32_e32 v5, 0, v3
	buffer_inv sc1
	v_rcp_iflag_f32_e32 v2, v2
	s_nop 0
	v_mul_f32_e32 v2, 0x4f7ffffe, v2
	v_cvt_u32_f32_e32 v2, v2
	v_mul_lo_u32 v5, v5, v2
	v_mul_hi_u32 v5, v2, v5
	v_add_u32_e32 v2, v2, v5
	s_waitcnt vmcnt(1)
	v_mul_hi_u32 v2, v4, v2
	v_mul_lo_u32 v5, v2, v3
	v_sub_u32_e32 v5, v4, v5
	v_add_u32_e32 v6, 1, v2
	v_cmp_ge_u32_e32 vcc, v5, v3
	v_add_u32_e32 v4, 1, v4
	s_nop 0
	v_cndmask_b32_e32 v2, v2, v6, vcc
	v_sub_u32_e32 v6, v5, v3
	v_cndmask_b32_e32 v5, v5, v6, vcc
	v_add_u32_e32 v6, 1, v2
	v_cmp_ge_u32_e32 vcc, v5, v3
	s_nop 1
	v_cndmask_b32_e32 v2, v2, v6, vcc
	v_mul_lo_u32 v5, v3, v2
	v_add_u32_e32 v3, v5, v3
	v_cmp_ne_u32_e32 vcc, v4, v3
	s_waitcnt lgkmcnt(0)
	v_add_u32_e32 v5, 1, v2
	v_mul_lo_u32 v5, v5, v1
	v_mov_b32_e32 v6, 0x3000
	v_mov_b32_e32 v8, 0
	s_cbranch_vccnz .Lxb1_spin
	buffer_wbl2 sc1
	s_waitcnt vmcnt(0)
	v_mov_b32_e32 v7, 1
	global_atomic_add v6, v7, s[58:59] offset:1024

; __global__ void __launch_bounds__(NWAVES * 64, 2) fwd(Args args) {
;     ...
;         if (whole && tid == 0) {
;             bool same = true;
;             for (int j = 0; j < 4; ++j) same = same && (__hip_atomic_load((unsigned*)(ctl + CW_XCCT) + (bx & 63) + 64 * j, RLX_AGENT) == bar.x + 1u);
;             if (!same) __hip_atomic_store((unsigned*)(ctl + CW_NONLOCAL), 1u, RLX_AGENT);
;         }
.LBB0_115:
	s_and_saveexec_b64 s[6:7], s[38:39]
	s_cbranch_execz .LBB0_122
	s_and_b32 s4, s2, 63
	s_add_i32 s3, s90, 1
	s_lshl_b32 s4, s4, 2
	s_add_u32 s8, s60, s4
	s_addc_u32 s9, s61, 0
	v_mov_b32_e32 v1, 0x28000
	global_load_dword v2, v1, s[8:9] sc1
	global_load_dword v3, v1, s[8:9] offset:256 sc1
	global_load_dword v4, v1, s[8:9] offset:512 sc1
	global_load_dword v5, v1, s[8:9] offset:768 sc1
	s_waitcnt vmcnt(0)
	v_cmp_ne_u32_e32 vcc, s3, v2
	v_cmp_ne_u32_e64 s[10:11], s3, v3
	s_or_b64 s[10:11], vcc, s[10:11]
	v_cmp_ne_u32_e32 vcc, s3, v4
	s_or_b64 s[10:11], vcc, s[10:11]
	v_cmp_ne_u32_e32 vcc, s3, v5
	s_or_b64 s[10:11], vcc, s[10:11]

; __device__ __forceinline__ unsigned xb_add(unsigned* p, unsigned v) { return __hip_atomic_fetch_add(p, v, __ATOMIC_RELAXED, __HIP_MEMORY_SCOPE_AGENT); }
; __device__ __forceinline__ void xcd_barrier(const XcdBarrier& b) {
;     asm volatile("s_waitcnt vmcnt(0)" ::: "memory");
;     __syncthreads();
;     if (threadIdx.x == 0) {
;         unsigned* bar = b.bar;
;         __builtin_amdgcn_s_waitcnt(0);
;         unsigned nloc = b.st[0], nx = b.st[1];
;         if (nloc == 0u) { xcd_barrier_complete(bar, b.x, nloc, nx); b.st[0] = nloc; b.st[1] = nx; }
;         const unsigned old = xb_add(&bar[XB_XSUB(b.x)], 1u);
;         asm volatile("buffer_inv sc1" ::: "memory");
;         const unsigned gen = old / nloc;
;         if (old + 1u == (gen + 1u) * nloc) {
;             __builtin_amdgcn_fence(__ATOMIC_RELEASE, "agent");
;             asm volatile("s_waitcnt vmcnt(0)" ::: "memory");
;             const unsigned og = xb_add(&bar[XB_TOP], 1u);
.LBB0_857:
	s_lshl_b32 s3, s90, 8
	s_add_u32 s6, s58, s3
	s_addc_u32 s7, s59, 0
	v_mov_b32_e32 v2, 0x1000
	v_mov_b32_e32 v4, 1
	global_atomic_add v4, v2, v4, s[6:7] offset:1024 sc0
	v_cvt_f32_u32_e32 v2, v3
	v_sub_u32_e32 v5, 0, v3
	buffer_inv sc1
	v_rcp_iflag_f32_e32 v2, v2
	s_nop 0
	v_mul_f32_e32 v2, 0x4f7ffffe, v2
	v_cvt_u32_f32_e32 v2, v2
	v_mul_lo_u32 v5, v5, v2
	v_mul_hi_u32 v5, v2, v5
	v_add_u32_e32 v2, v2, v5
	s_waitcnt vmcnt(1)
	v_mul_hi_u32 v2, v4, v2
	v_mul_lo_u32 v5, v2, v3
	v_sub_u32_e32 v5, v4, v5
	v_add_u32_e32 v6, 1, v2
	v_cmp_ge_u32_e32 vcc, v5, v3
	v_add_u32_e32 v4, 1, v4
	s_nop 0
	v_cndmask_b32_e32 v2, v2, v6, vcc
	v_sub_u32_e32 v6, v5, v3
	v_cndmask_b32_e32 v5, v5, v6, vcc
	v_add_u32_e32 v6, 1, v2
	v_cmp_ge_u32_e32 vcc, v5, v3
	s_nop 1
	v_cndmask_b32_e32 v2, v2, v6, vcc
	v_mul_lo_u32 v5, v3, v2
	v_add_u32_e32 v3, v5, v3
	v_cmp_ne_u32_e32 vcc, v4, v3
	s_waitcnt lgkmcnt(0)
	v_add_u32_e32 v5, 1, v2
	v_mul_lo_u32 v5, v5, v1
	v_mov_b32_e32 v6, 0x3000
	v_mov_b32_e32 v8, 0
	s_cbranch_vccnz .Lxb4_spin
	buffer_wbl2 sc1
	s_waitcnt vmcnt(0)
	v_mov_b32_e32 v7, 1
	global_atomic_add v6, v7, s[58:59] offset:1024

; __device__ __forceinline__ unsigned xb_add(unsigned* p, unsigned v) { return __hip_atomic_fetch_add(p, v, __ATOMIC_RELAXED, __HIP_MEMORY_SCOPE_AGENT); }
; __device__ __forceinline__ void xcd_barrier(const XcdBarrier& b) {
;     asm volatile("s_waitcnt vmcnt(0)" ::: "memory");
;     __syncthreads();
;     if (threadIdx.x == 0) {
;         unsigned* bar = b.bar;
;         __builtin_amdgcn_s_waitcnt(0);
;         unsigned nloc = b.st[0], nx = b.st[1];
;         if (nloc == 0u) { xcd_barrier_complete(bar, b.x, nloc, nx); b.st[0] = nloc; b.st[1] = nx; }
;         const unsigned old = xb_add(&bar[XB_XSUB(b.x)], 1u);
;         asm volatile("buffer_inv sc1" ::: "memory");
;         const unsigned gen = old / nloc;
;         if (old + 1u == (gen + 1u) * nloc) {
;             __builtin_amdgcn_fence(__ATOMIC_RELEASE, "agent");
;             asm volatile("s_waitcnt vmcnt(0)" ::: "memory");
;             const unsigned og = xb_add(&bar[XB_TOP], 1u);
.LBB0_1040:
	s_lshl_b32 s5, s90, 8
	s_add_u32 s6, s58, s5
	s_addc_u32 s7, s59, 0
	v_mov_b32_e32 v2, 0x1000
	v_mov_b32_e32 v4, 1
	global_atomic_add v4, v2, v4, s[6:7] offset:1024 sc0
	v_cvt_f32_u32_e32 v2, v3
	v_sub_u32_e32 v5, 0, v3
	buffer_inv sc1
	v_rcp_iflag_f32_e32 v2, v2
	s_nop 0
	v_mul_f32_e32 v2, 0x4f7ffffe, v2
	v_cvt_u32_f32_e32 v2, v2
	v_mul_lo_u32 v5, v5, v2
	v_mul_hi_u32 v5, v2, v5
	v_add_u32_e32 v2, v2, v5
	s_waitcnt vmcnt(1)
	v_mul_hi_u32 v2, v4, v2
	v_mul_lo_u32 v5, v2, v3
	v_sub_u32_e32 v5, v4, v5
	v_add_u32_e32 v6, 1, v2
	v_cmp_ge_u32_e32 vcc, v5, v3
	v_add_u32_e32 v4, 1, v4
	s_nop 0
	v_cndmask_b32_e32 v2, v2, v6, vcc
	v_sub_u32_e32 v6, v5, v3
	v_cndmask_b32_e32 v5, v5, v6, vcc
	v_add_u32_e32 v6, 1, v2
	v_cmp_ge_u32_e32 vcc, v5, v3
	s_nop 1
	v_cndmask_b32_e32 v2, v2, v6, vcc
	v_mul_lo_u32 v5, v3, v2
	v_add_u32_e32 v3, v5, v3
	v_cmp_ne_u32_e32 vcc, v4, v3
	s_waitcnt lgkmcnt(0)
	v_add_u32_e32 v5, 1, v2
	v_mul_lo_u32 v5, v5, v1
	v_mov_b32_e32 v6, 0x3000
	v_mov_b32_e32 v8, 0
	s_cbranch_vccnz .Lxb6_spin
	buffer_wbl2 sc1
	s_waitcnt vmcnt(0)
	v_mov_b32_e32 v7, 1
	global_atomic_add v6, v7, s[58:59] offset:1024

; __device__ __forceinline__ unsigned xb_ld(unsigned* p)              { return __hip_atomic_load(p, __ATOMIC_RELAXED, __HIP_MEMORY_SCOPE_AGENT); }
; #define XB_SPIN(cond, bar) do { unsigned _sp = 0; while (cond) { __builtin_amdgcn_s_sleep(1); \
;     if ((++_sp & 255u) == 0u) { if (xb_ld(&(bar)[XB_TMO])) break; if (_sp > XB_SPIN_CAP) { atomicAdd(&(bar)[XB_TMO], 1u); break; } } } } while (0)
; __global__ void __launch_bounds__(NWAVES * 64, 2) fwd(Args args) {
;     ...
;         if (MISC[10] != 0u && team_pm >= 32) { if (tid == 0) { const int q_ = 2 * (team_pm - 32);
;                 XB_SPIN(xb_ld((unsigned*)(ctl + CW_TEAM) + 32 * q_) < 4u, bar.bar); XB_SPIN(xb_ld((unsigned*)(ctl + CW_TEAM) + 32 * (q_ + 1)) < 4u, bar.bar); }
;             __syncthreads(); }
.LBB0_1201:
.LBB0_1202:
	s_cmp_lt_i32 s56, 8
	s_cselect_b64 s[0:1], -1, 0
	s_cmp_gt_i32 s57, 7
	s_cselect_b64 s[6:7], -1, 0
	s_and_b64 s[0:1], s[0:1], s[6:7]
	s_andn2_b64 vcc, exec, s[0:1]
	s_cbranch_vccnz .LBB0_1322
	s_add_i32 s0, 0, 0x22968
	s_waitcnt vmcnt(0)
	v_mov_b32_e32 v1, s0
	ds_read_b32 v1, v1
	s_cmp_gt_u32 s4, 31
	s_cselect_b64 s[0:1], -1, 0
	s_waitcnt lgkmcnt(0)
	v_cmp_ne_u32_e32 vcc, 0, v1
	s_and_b64 s[0:1], vcc, s[0:1]
	s_andn2_b64 vcc, exec, s[0:1]
	s_cbranch_vccnz .LBB0_1231
	s_and_saveexec_b64 s[0:1], s[96:97]
	s_cbranch_execz .LBB0_1230
	s_lshl_b32 s4, s3, 8
	s_add_u32 s6, s60, s4
	s_addc_u32 s7, s61, 0
	v_mov_b32_e32 v1, 0x1e000
	v_mov_b32_e32 v3, 0x1e080
	global_load_dword v1, v1, s[6:7] sc1
	global_load_dword v3, v3, s[6:7] sc1
	s_add_u32 s4, s6, 0x20000
	s_addc_u32 s5, s7, 0
	s_add_u32 s6, s6, 0x1e000
	s_addc_u32 s7, s7, 0
	s_waitcnt vmcnt(0)
	v_cmp_lt_u32_e32 vcc, 3, v1
	s_cbranch_vccnz .LBB0_1218
	s_mov_b32 s18, 1
	v_mov_b32_e32 v1, 0
	s_branch .LBB0_1208

; __device__ __forceinline__ unsigned xb_ld(unsigned* p)              { return __hip_atomic_load(p, __ATOMIC_RELAXED, __HIP_MEMORY_SCOPE_AGENT); }
; #define XB_SPIN(cond, bar) do { unsigned _sp = 0; while (cond) { __builtin_amdgcn_s_sleep(1); \
;     if ((++_sp & 255u) == 0u) { if (xb_ld(&(bar)[XB_TMO])) break; if (_sp > XB_SPIN_CAP) { atomicAdd(&(bar)[XB_TMO], 1u); break; } } } } while (0)
; __global__ void __launch_bounds__(NWAVES * 64, 2) fwd(Args args) {
;     ...
;                 XB_SPIN(xb_ld((unsigned*)(ctl + CW_TEAM) + 32 * q_) < 4u, bar.bar); XB_SPIN(xb_ld((unsigned*)(ctl + CW_TEAM) + 32 * (q_ + 1)) < 4u, bar.bar); }
.LBB0_1218:
	s_add_u32 s6, s4, 0xffffe080
	s_addc_u32 s7, s5, -1
	v_mov_b32_e32 v1, 0
	v_mov_b32_e32 v2, v3
	v_cmp_lt_u32_e32 vcc, 3, v2
	s_cbranch_vccnz .LBB0_1230
	s_mov_b32 s4, 1
	s_branch .LBB0_1221

; __device__ __forceinline__ unsigned xb_add(unsigned* p, unsigned v) { return __hip_atomic_fetch_add(p, v, __ATOMIC_RELAXED, __HIP_MEMORY_SCOPE_AGENT); }
; __device__ __forceinline__ void xcd_barrier(const XcdBarrier& b) {
;     asm volatile("s_waitcnt vmcnt(0)" ::: "memory");
;     __syncthreads();
;     if (threadIdx.x == 0) {
;         unsigned* bar = b.bar;
;         __builtin_amdgcn_s_waitcnt(0);
;         unsigned nloc = b.st[0], nx = b.st[1];
;         if (nloc == 0u) { xcd_barrier_complete(bar, b.x, nloc, nx); b.st[0] = nloc; b.st[1] = nx; }
;         const unsigned old = xb_add(&bar[XB_XSUB(b.x)], 1u);
;         asm volatile("buffer_inv sc1" ::: "memory");
;         const unsigned gen = old / nloc;
;         if (old + 1u == (gen + 1u) * nloc) {
;             __builtin_amdgcn_fence(__ATOMIC_RELEASE, "agent");
;             asm volatile("s_waitcnt vmcnt(0)" ::: "memory");
;             const unsigned og = xb_add(&bar[XB_TOP], 1u);
.LBB0_1288:
	s_lshl_b32 s3, s90, 8
	s_add_u32 s4, s58, s3
	s_addc_u32 s5, s59, 0
	v_mov_b32_e32 v2, 0x1000
	v_mov_b32_e32 v4, 1
	global_atomic_add v4, v2, v4, s[4:5] offset:1024 sc0
	v_cvt_f32_u32_e32 v2, v3
	v_sub_u32_e32 v5, 0, v3
	buffer_inv sc1
	v_rcp_iflag_f32_e32 v2, v2
	s_nop 0
	v_mul_f32_e32 v2, 0x4f7ffffe, v2
	v_cvt_u32_f32_e32 v2, v2
	v_mul_lo_u32 v5, v5, v2
	v_mul_hi_u32 v5, v2, v5
	v_add_u32_e32 v2, v2, v5
	s_waitcnt vmcnt(1)
	v_mul_hi_u32 v2, v4, v2
	v_mul_lo_u32 v5, v2, v3
	v_sub_u32_e32 v5, v4, v5
	v_add_u32_e32 v6, 1, v2
	v_cmp_ge_u32_e32 vcc, v5, v3
	v_add_u32_e32 v4, 1, v4
	s_nop 0
	v_cndmask_b32_e32 v2, v2, v6, vcc
	v_sub_u32_e32 v6, v5, v3
	v_cndmask_b32_e32 v5, v5, v6, vcc
	v_add_u32_e32 v6, 1, v2
	v_cmp_ge_u32_e32 vcc, v5, v3
	s_nop 1
	v_cndmask_b32_e32 v2, v2, v6, vcc
	v_mul_lo_u32 v5, v3, v2
	v_add_u32_e32 v3, v5, v3
	v_cmp_ne_u32_e32 vcc, v4, v3
	s_waitcnt lgkmcnt(0)
	v_add_u32_e32 v5, 1, v2
	v_mul_lo_u32 v5, v5, v1
	v_mov_b32_e32 v6, 0x3000
	v_mov_b32_e32 v8, 0
	s_cbranch_vccnz .Lxb8_spin
	buffer_wbl2 sc1
	s_waitcnt vmcnt(0)
	v_mov_b32_e32 v7, 1
	global_atomic_add v6, v7, s[58:59] offset:1024
